# attention unit prologues: no wait for the previous stores' acknowledgements before issuing the first loads
# speedup vs baseline: 1.0017x; 1.0017x over previous
.LBB0_214:
	s_lshl_b32 s40, s56, 3
	s_ashr_i32 s41, s40, 31
	v_lshl_add_u64 v[182:183], s[40:41], 1, v[192:193]
	s_lshl_b32 s40, s56, 4
	v_and_or_b32 v0, s40, 48, v198
	s_ashr_i32 s40, s42, 3
	s_andn2_b32 s40, s40, 31
	v_lshlrev_b32_e32 v0, 8, v0
	s_ashr_i32 s41, s40, 31
	s_lshl_b32 s43, s56, 10
	s_nop 0
	v_lshl_add_u64 v[2:3], s[6:7], 0, v[0:1]
	s_cmp_lg_u32 0, -1
	v_lshl_add_u64 v[2:3], s[40:41], 1, v[2:3]
	s_cselect_b32 s40, 0, 0
	v_mov_b32_e32 v191, v1
	s_add_i32 s60, s43, s40
	v_cndmask_b32_e64 v0, 0, 1, s[36:37]
	v_lshl_add_u64 v[184:185], v[2:3], 0, v[190:191]
	v_cmp_ne_u32_e64 s[40:41], 1, v0
	s_andn2_b64 vcc, exec, s[36:37]
	s_add_i32 s61, s60, 0x6000
	s_cbranch_vccnz .LBB0_216
	s_mov_b32 s36, m0
	s_mov_b32 m0, s60
	s_nop 0
	global_load_lds_dwordx4 v[182:183], off
	s_mov_b32 m0, s36
	s_cmp_lg_u32 0, -1
	s_mov_b32 s36, m0
	s_mov_b32 m0, s61
	s_nop 0
	global_load_lds_dwordx4 v[184:185], off
	s_mov_b32 m0, s36
	s_mov_b64 s[36:37], 0x4000
	v_lshl_add_u64 v[2:3], v[182:183], 0, s[36:37]
	s_cselect_b32 s36, 0, 0
	s_add_i32 s36, s36, s43
	s_addk_i32 s36, 0x2000
	s_mov_b32 s37, m0
	s_mov_b32 m0, s36
	s_nop 0
	global_load_lds_dwordx4 v[2:3], off
	s_mov_b32 m0, s37

.LBB0_244:
	s_lshl_b32 s2, s56, 1
	s_add_i32 s2, s2, -8
	v_and_or_b32 v0, s34, 32, v198
	s_lshl_b32 s54, s2, 4
	v_lshlrev_b32_e32 v0, 8, v0
	s_nop 0
	v_lshl_add_u64 v[8:9], v[192:193], 0, s[54:55]
	v_lshl_add_u64 v[4:5], s[6:7], 0, v[0:1]
	s_andn2_b32 s54, s54, 63
	s_add_i32 s3, s34, 0xffffff90
	v_lshl_add_u64 v[4:5], v[4:5], 0, s[54:55]
	v_and_or_b32 v0, s3, 48, v198
	s_and_b32 s54, s3, 0xffffffc0
	s_lshl_b32 s2, s2, 10
	v_lshlrev_b32_e32 v0, 8, v0
	s_cmp_lg_u32 0, -1
	v_lshl_add_u64 v[6:7], s[6:7], 0, v[0:1]
	s_cselect_b32 s6, 0, 0
	s_add_i32 s7, s2, s6
	s_mov_b32 s2, m0
	s_mov_b32 m0, s7
	s_nop 0
	global_load_lds_dwordx4 v[8:9], off
	s_mov_b32 m0, s2
	v_lshl_add_u64 v[2:3], v[8:9], 0, 16
	v_mov_b32_e32 v191, v1
	s_add_i32 s36, s7, 0x400
	s_mov_b32 s2, m0
	s_mov_b32 m0, s36
	s_nop 0
	global_load_lds_dwordx4 v[2:3], off
	s_mov_b32 m0, s2
	v_lshl_add_u64 v[4:5], v[4:5], 0, v[190:191]
	v_lshl_add_u64 v[6:7], v[6:7], 0, s[54:55]
	s_add_i32 s34, s7, 0x6000
	s_mov_b32 s2, m0
	s_mov_b32 m0, s34
	s_nop 0
	global_load_lds_dwordx4 v[4:5], off
	s_mov_b32 m0, s2
	v_lshl_add_u64 v[6:7], v[6:7], 0, v[190:191]
	s_add_i32 s35, s7, 0x6400
	s_mov_b32 s2, m0
	s_mov_b32 m0, s35
	s_nop 0
	global_load_lds_dwordx4 v[6:7], off
	s_mov_b32 m0, s2
	s_mov_b64 s[38:39], 0x4000
	v_lshl_add_u64 v[2:3], v[8:9], 0, s[38:39]
	s_add_i32 s2, s7, 0x2000
	s_mov_b32 s3, m0
	s_mov_b32 m0, s2
	s_nop 0
	global_load_lds_dwordx4 v[2:3], off
	s_mov_b32 m0, s3
	s_mov_b64 s[2:3], 0x4010
	v_lshl_add_u64 v[2:3], v[8:9], 0, s[2:3]
	s_add_i32 s2, s7, 0x2400
	s_mov_b32 s3, m0
	s_mov_b32 m0, s2
	s_nop 0
	global_load_lds_dwordx4 v[2:3], off
	s_mov_b32 m0, s3
	v_lshl_add_u64 v[2:3], v[4:5], 0, s[38:39]
	s_add_i32 s2, s7, 0x8000
	s_mov_b32 s3, m0
	s_mov_b32 m0, s2
	s_nop 0
	global_load_lds_dwordx4 v[2:3], off
	s_mov_b32 m0, s3
	v_lshl_add_u64 v[2:3], v[6:7], 0, s[38:39]
	s_add_i32 s2, s7, 0x8400
	s_mov_b32 s3, m0
	s_mov_b32 m0, s2
	s_nop 0
	global_load_lds_dwordx4 v[2:3], off
	s_mov_b32 m0, s3
	s_mov_b64 s[38:39], 0x8000
	v_lshl_add_u64 v[2:3], v[8:9], 0, s[38:39]
	s_add_i32 s2, s7, 0x4000
	s_mov_b32 s3, m0
	s_mov_b32 m0, s2
	s_nop 0
	global_load_lds_dwordx4 v[2:3], off
	s_mov_b32 m0, s3
	s_mov_b64 s[2:3], 0x8010
	v_lshl_add_u64 v[2:3], v[8:9], 0, s[2:3]
	s_add_i32 s2, s7, 0x4400
	s_mov_b32 s3, m0
	s_mov_b32 m0, s2
	s_nop 0
	global_load_lds_dwordx4 v[2:3], off
	s_mov_b32 m0, s3
	s_waitcnt vmcnt(8) lgkmcnt(0)
	s_barrier
	s_waitcnt vmcnt(0) lgkmcnt(0)
	s_barrier
	v_lshl_add_u64 v[2:3], v[4:5], 0, s[38:39]
	s_add_i32 s2, s7, 0xa000
	s_mov_b32 s3, m0
	s_mov_b32 m0, s2
	s_nop 0
	global_load_lds_dwordx4 v[2:3], off
	s_mov_b32 m0, s3
	v_lshl_add_u64 v[2:3], v[6:7], 0, s[38:39]
	s_add_i32 s2, s7, 0xa400
	s_mov_b32 s3, m0
	s_mov_b32 m0, s2
	s_nop 0
	global_load_lds_dwordx4 v[2:3], off
	s_mov_b32 m0, s3
	s_mov_b64 s[38:39], 0xc000
	v_lshl_add_u64 v[2:3], v[8:9], 0, s[38:39]
	s_mov_b32 s2, m0
	s_mov_b32 m0, s7
	s_nop 0
	global_load_lds_dwordx4 v[2:3], off
	s_mov_b32 m0, s2
	s_mov_b64 s[2:3], 0xc010
	v_lshl_add_u64 v[2:3], v[8:9], 0, s[2:3]
	s_mov_b32 s2, m0
	s_mov_b32 m0, s36
	s_nop 0
	global_load_lds_dwordx4 v[2:3], off
	s_mov_b32 m0, s2
	s_mov_b64 s[2:3], 0x10010
	v_lshl_add_u64 v[2:3], v[4:5], 0, s[38:39]
	v_lshl_add_u64 v[4:5], v[6:7], 0, s[38:39]
	v_lshl_add_u64 v[6:7], v[8:9], 0, s[2:3]
	s_mov_b64 s[2:3], 0x10000
	s_waitcnt vmcnt(4) lgkmcnt(0)
	s_barrier
	v_lshl_add_u64 v[8:9], v[8:9], 0, s[2:3]
	s_lshl_b32 s2, s53, 14
	s_lshl_b32 s36, s56, 11
	s_add_i32 s2, s2, 0xffff0000
	s_mov_b32 s30, 4
	s_movk_i32 s31, 0x6000
	s_mov_b64 s[90:91], 0x8000
	s_add_i32 s36, s36, s6
	s_add_u32 s37, s2, 0x4000
	s_mov_b64 s[2:3], 0
	s_branch .LBB0_246
